# phase-0 adaLN item: conditioning loads issued together and the GEMV weight stream kept 16 loads deep (same accumulation order)
# baseline (speedup 1.0000x reference)
.LBB0_530:
	s_and_b64 vcc, exec, s[4:5]
	s_cbranch_vccz .LBB0_479
	v_mov_b64_e32 v[2:3], v[10:11]
	global_load_dword v26, v[2:3], off
	global_load_dword v27, v[2:3], off offset:1024
	global_load_dword v28, v[2:3], off offset:2048
	global_load_dword v29, v[2:3], off offset:3072
	v_add_co_u32_e32 v2, vcc, 0x1000, v2
	v_addc_co_u32_e32 v3, vcc, 0, v3, vcc
	global_load_dword v30, v[2:3], off
	global_load_dword v31, v[2:3], off offset:1024
	global_load_dword v32, v[2:3], off offset:2048
	global_load_dword v33, v[2:3], off offset:3072
	v_add_co_u32_e32 v2, vcc, 0x1000, v2
	v_addc_co_u32_e32 v3, vcc, 0, v3, vcc
	global_load_dword v34, v[2:3], off
	global_load_dword v35, v[2:3], off offset:1024
	global_load_dword v36, v[2:3], off offset:2048
	global_load_dword v37, v[2:3], off offset:3072
	v_add_co_u32_e32 v2, vcc, 0x1000, v2
	v_addc_co_u32_e32 v3, vcc, 0, v3, vcc
	global_load_dword v38, v[2:3], off
	global_load_dword v39, v[2:3], off offset:1024
	global_load_dword v40, v[2:3], off offset:2048
	global_load_dword v41, v[2:3], off offset:3072
	v_lshlrev_b32_e32 v0, 2, v6
	global_load_dword v42, v0, s[66:67]
	global_load_dword v43, v0, s[66:67] offset:1024
	global_load_dword v44, v0, s[66:67] offset:2048
	global_load_dword v45, v0, s[66:67] offset:3072
	s_waitcnt vmcnt(19)
	v_mul_f32_e32 v14, 0xbfb8aa3b, v26
	v_exp_f32_e32 v14, v14
	s_nop 0
	v_add_f32_e32 v14, 1.0, v14
	v_div_scale_f32 v15, s[10:11], v14, v14, v26
	v_rcp_f32_e32 v16, v15
	v_div_scale_f32 v17, vcc, v26, v14, v26
	v_fma_f32 v18, -v15, v16, 1.0
	v_fmac_f32_e32 v16, v18, v16
	v_mul_f32_e32 v18, v17, v16
	v_fma_f32 v19, -v15, v18, v17
	v_fmac_f32_e32 v18, v19, v16
	v_fma_f32 v15, -v15, v18, v17
	v_div_fmas_f32 v15, v15, v16, v18
	v_div_fixup_f32 v26, v15, v14, v26
	ds_write_b32 v22, v26
	s_waitcnt vmcnt(18)
	v_mul_f32_e32 v14, 0xbfb8aa3b, v27
	v_exp_f32_e32 v14, v14
	s_nop 0
	v_add_f32_e32 v14, 1.0, v14
	v_div_scale_f32 v15, s[10:11], v14, v14, v27
	v_rcp_f32_e32 v16, v15
	v_div_scale_f32 v17, vcc, v27, v14, v27
	v_fma_f32 v18, -v15, v16, 1.0
	v_fmac_f32_e32 v16, v18, v16
	v_mul_f32_e32 v18, v17, v16
	v_fma_f32 v19, -v15, v18, v17
	v_fmac_f32_e32 v18, v19, v16
	v_fma_f32 v15, -v15, v18, v17
	v_div_fmas_f32 v15, v15, v16, v18
	v_div_fixup_f32 v27, v15, v14, v27
	ds_write_b32 v22, v27 offset:1024
	s_waitcnt vmcnt(17)
	v_mul_f32_e32 v14, 0xbfb8aa3b, v28
	v_exp_f32_e32 v14, v14
	s_nop 0
	v_add_f32_e32 v14, 1.0, v14
	v_div_scale_f32 v15, s[10:11], v14, v14, v28
	v_rcp_f32_e32 v16, v15
	v_div_scale_f32 v17, vcc, v28, v14, v28
	v_fma_f32 v18, -v15, v16, 1.0
	v_fmac_f32_e32 v16, v18, v16
	v_mul_f32_e32 v18, v17, v16
	v_fma_f32 v19, -v15, v18, v17
	v_fmac_f32_e32 v18, v19, v16
	v_fma_f32 v15, -v15, v18, v17
	v_div_fmas_f32 v15, v15, v16, v18
	v_div_fixup_f32 v28, v15, v14, v28
	ds_write_b32 v22, v28 offset:2048
	s_waitcnt vmcnt(16)
	v_mul_f32_e32 v14, 0xbfb8aa3b, v29
	v_exp_f32_e32 v14, v14
	s_nop 0
	v_add_f32_e32 v14, 1.0, v14
	v_div_scale_f32 v15, s[10:11], v14, v14, v29
	v_rcp_f32_e32 v16, v15
	v_div_scale_f32 v17, vcc, v29, v14, v29
	v_fma_f32 v18, -v15, v16, 1.0
	v_fmac_f32_e32 v16, v18, v16
	v_mul_f32_e32 v18, v17, v16
	v_fma_f32 v19, -v15, v18, v17
	v_fmac_f32_e32 v18, v19, v16
	v_fma_f32 v15, -v15, v18, v17
	v_div_fmas_f32 v15, v15, v16, v18
	v_div_fixup_f32 v29, v15, v14, v29
	ds_write_b32 v22, v29 offset:3072
	s_waitcnt vmcnt(15)
	v_mul_f32_e32 v14, 0xbfb8aa3b, v30
	v_exp_f32_e32 v14, v14
	s_nop 0
	v_add_f32_e32 v14, 1.0, v14
	v_div_scale_f32 v15, s[10:11], v14, v14, v30
	v_rcp_f32_e32 v16, v15
	v_div_scale_f32 v17, vcc, v30, v14, v30
	v_fma_f32 v18, -v15, v16, 1.0
	v_fmac_f32_e32 v16, v18, v16
	v_mul_f32_e32 v18, v17, v16
	v_fma_f32 v19, -v15, v18, v17
	v_fmac_f32_e32 v18, v19, v16
	v_fma_f32 v15, -v15, v18, v17
	v_div_fmas_f32 v15, v15, v16, v18
	v_div_fixup_f32 v30, v15, v14, v30
	ds_write_b32 v22, v30 offset:4096
	s_waitcnt vmcnt(14)
	v_mul_f32_e32 v14, 0xbfb8aa3b, v31
	v_exp_f32_e32 v14, v14
	s_nop 0
	v_add_f32_e32 v14, 1.0, v14
	v_div_scale_f32 v15, s[10:11], v14, v14, v31
	v_rcp_f32_e32 v16, v15
	v_div_scale_f32 v17, vcc, v31, v14, v31
	v_fma_f32 v18, -v15, v16, 1.0
	v_fmac_f32_e32 v16, v18, v16
	v_mul_f32_e32 v18, v17, v16
	v_fma_f32 v19, -v15, v18, v17
	v_fmac_f32_e32 v18, v19, v16
	v_fma_f32 v15, -v15, v18, v17
	v_div_fmas_f32 v15, v15, v16, v18
	v_div_fixup_f32 v31, v15, v14, v31
	ds_write_b32 v22, v31 offset:5120
	s_waitcnt vmcnt(13)
	v_mul_f32_e32 v14, 0xbfb8aa3b, v32
	v_exp_f32_e32 v14, v14
	s_nop 0
	v_add_f32_e32 v14, 1.0, v14
	v_div_scale_f32 v15, s[10:11], v14, v14, v32
	v_rcp_f32_e32 v16, v15
	v_div_scale_f32 v17, vcc, v32, v14, v32
	v_fma_f32 v18, -v15, v16, 1.0
	v_fmac_f32_e32 v16, v18, v16
	v_mul_f32_e32 v18, v17, v16
	v_fma_f32 v19, -v15, v18, v17
	v_fmac_f32_e32 v18, v19, v16
	v_fma_f32 v15, -v15, v18, v17
	v_div_fmas_f32 v15, v15, v16, v18
	v_div_fixup_f32 v32, v15, v14, v32
	ds_write_b32 v22, v32 offset:6144
	s_waitcnt vmcnt(12)
	v_mul_f32_e32 v14, 0xbfb8aa3b, v33
	v_exp_f32_e32 v14, v14
	s_nop 0
	v_add_f32_e32 v14, 1.0, v14
	v_div_scale_f32 v15, s[10:11], v14, v14, v33
	v_rcp_f32_e32 v16, v15
	v_div_scale_f32 v17, vcc, v33, v14, v33
	v_fma_f32 v18, -v15, v16, 1.0
	v_fmac_f32_e32 v16, v18, v16
	v_mul_f32_e32 v18, v17, v16
	v_fma_f32 v19, -v15, v18, v17
	v_fmac_f32_e32 v18, v19, v16
	v_fma_f32 v15, -v15, v18, v17
	v_div_fmas_f32 v15, v15, v16, v18
	v_div_fixup_f32 v33, v15, v14, v33
	ds_write_b32 v22, v33 offset:7168
	s_waitcnt vmcnt(11)
	v_mul_f32_e32 v14, 0xbfb8aa3b, v34
	v_exp_f32_e32 v14, v14
	s_nop 0
	v_add_f32_e32 v14, 1.0, v14
	v_div_scale_f32 v15, s[10:11], v14, v14, v34
	v_rcp_f32_e32 v16, v15
	v_div_scale_f32 v17, vcc, v34, v14, v34
	v_fma_f32 v18, -v15, v16, 1.0
	v_fmac_f32_e32 v16, v18, v16
	v_mul_f32_e32 v18, v17, v16
	v_fma_f32 v19, -v15, v18, v17
	v_fmac_f32_e32 v18, v19, v16
	v_fma_f32 v15, -v15, v18, v17
	v_div_fmas_f32 v15, v15, v16, v18
	v_div_fixup_f32 v34, v15, v14, v34
	ds_write_b32 v22, v34 offset:8192
	s_waitcnt vmcnt(10)
	v_mul_f32_e32 v14, 0xbfb8aa3b, v35
	v_exp_f32_e32 v14, v14
	s_nop 0
	v_add_f32_e32 v14, 1.0, v14
	v_div_scale_f32 v15, s[10:11], v14, v14, v35
	v_rcp_f32_e32 v16, v15
	v_div_scale_f32 v17, vcc, v35, v14, v35
	v_fma_f32 v18, -v15, v16, 1.0
	v_fmac_f32_e32 v16, v18, v16
	v_mul_f32_e32 v18, v17, v16
	v_fma_f32 v19, -v15, v18, v17
	v_fmac_f32_e32 v18, v19, v16
	v_fma_f32 v15, -v15, v18, v17
	v_div_fmas_f32 v15, v15, v16, v18
	v_div_fixup_f32 v35, v15, v14, v35
	ds_write_b32 v22, v35 offset:9216
	s_waitcnt vmcnt(9)
	v_mul_f32_e32 v14, 0xbfb8aa3b, v36
	v_exp_f32_e32 v14, v14
	s_nop 0
	v_add_f32_e32 v14, 1.0, v14
	v_div_scale_f32 v15, s[10:11], v14, v14, v36
	v_rcp_f32_e32 v16, v15
	v_div_scale_f32 v17, vcc, v36, v14, v36
	v_fma_f32 v18, -v15, v16, 1.0
	v_fmac_f32_e32 v16, v18, v16
	v_mul_f32_e32 v18, v17, v16
	v_fma_f32 v19, -v15, v18, v17
	v_fmac_f32_e32 v18, v19, v16
	v_fma_f32 v15, -v15, v18, v17
	v_div_fmas_f32 v15, v15, v16, v18
	v_div_fixup_f32 v36, v15, v14, v36
	ds_write_b32 v22, v36 offset:10240
	s_waitcnt vmcnt(8)
	v_mul_f32_e32 v14, 0xbfb8aa3b, v37
	v_exp_f32_e32 v14, v14
	s_nop 0
	v_add_f32_e32 v14, 1.0, v14
	v_div_scale_f32 v15, s[10:11], v14, v14, v37
	v_rcp_f32_e32 v16, v15
	v_div_scale_f32 v17, vcc, v37, v14, v37
	v_fma_f32 v18, -v15, v16, 1.0
	v_fmac_f32_e32 v16, v18, v16
	v_mul_f32_e32 v18, v17, v16
	v_fma_f32 v19, -v15, v18, v17
	v_fmac_f32_e32 v18, v19, v16
	v_fma_f32 v15, -v15, v18, v17
	v_div_fmas_f32 v15, v15, v16, v18
	v_div_fixup_f32 v37, v15, v14, v37
	ds_write_b32 v22, v37 offset:11264
	s_waitcnt vmcnt(7)
	v_mul_f32_e32 v14, 0xbfb8aa3b, v38
	v_exp_f32_e32 v14, v14
	s_nop 0
	v_add_f32_e32 v14, 1.0, v14
	v_div_scale_f32 v15, s[10:11], v14, v14, v38
	v_rcp_f32_e32 v16, v15
	v_div_scale_f32 v17, vcc, v38, v14, v38
	v_fma_f32 v18, -v15, v16, 1.0
	v_fmac_f32_e32 v16, v18, v16
	v_mul_f32_e32 v18, v17, v16
	v_fma_f32 v19, -v15, v18, v17
	v_fmac_f32_e32 v18, v19, v16
	v_fma_f32 v15, -v15, v18, v17
	v_div_fmas_f32 v15, v15, v16, v18
	v_div_fixup_f32 v38, v15, v14, v38
	ds_write_b32 v22, v38 offset:12288
	s_waitcnt vmcnt(6)
	v_mul_f32_e32 v14, 0xbfb8aa3b, v39
	v_exp_f32_e32 v14, v14
	s_nop 0
	v_add_f32_e32 v14, 1.0, v14
	v_div_scale_f32 v15, s[10:11], v14, v14, v39
	v_rcp_f32_e32 v16, v15
	v_div_scale_f32 v17, vcc, v39, v14, v39
	v_fma_f32 v18, -v15, v16, 1.0
	v_fmac_f32_e32 v16, v18, v16
	v_mul_f32_e32 v18, v17, v16
	v_fma_f32 v19, -v15, v18, v17
	v_fmac_f32_e32 v18, v19, v16
	v_fma_f32 v15, -v15, v18, v17
	v_div_fmas_f32 v15, v15, v16, v18
	v_div_fixup_f32 v39, v15, v14, v39
	ds_write_b32 v22, v39 offset:13312
	s_waitcnt vmcnt(5)
	v_mul_f32_e32 v14, 0xbfb8aa3b, v40
	v_exp_f32_e32 v14, v14
	s_nop 0
	v_add_f32_e32 v14, 1.0, v14
	v_div_scale_f32 v15, s[10:11], v14, v14, v40
	v_rcp_f32_e32 v16, v15
	v_div_scale_f32 v17, vcc, v40, v14, v40
	v_fma_f32 v18, -v15, v16, 1.0
	v_fmac_f32_e32 v16, v18, v16
	v_mul_f32_e32 v18, v17, v16
	v_fma_f32 v19, -v15, v18, v17
	v_fmac_f32_e32 v18, v19, v16
	v_fma_f32 v15, -v15, v18, v17
	v_div_fmas_f32 v15, v15, v16, v18
	v_div_fixup_f32 v40, v15, v14, v40
	ds_write_b32 v22, v40 offset:14336
	s_waitcnt vmcnt(4)
	v_mul_f32_e32 v14, 0xbfb8aa3b, v41
	v_exp_f32_e32 v14, v14
	s_nop 0
	v_add_f32_e32 v14, 1.0, v14
	v_div_scale_f32 v15, s[10:11], v14, v14, v41
	v_rcp_f32_e32 v16, v15
	v_div_scale_f32 v17, vcc, v41, v14, v41
	v_fma_f32 v18, -v15, v16, 1.0
	v_fmac_f32_e32 v16, v18, v16
	v_mul_f32_e32 v18, v17, v16
	v_fma_f32 v19, -v15, v18, v17
	v_fmac_f32_e32 v18, v19, v16
	v_fma_f32 v15, -v15, v18, v17
	v_div_fmas_f32 v15, v15, v16, v18
	v_div_fixup_f32 v41, v15, v14, v41
	ds_write_b32 v22, v41 offset:15360
	s_waitcnt vmcnt(3)
	v_mul_f32_e32 v14, 0xbfb8aa3b, v42
	v_exp_f32_e32 v14, v14
	s_nop 0
	v_add_f32_e32 v14, 1.0, v14
	v_div_scale_f32 v15, s[10:11], v14, v14, v42
	v_rcp_f32_e32 v16, v15
	v_div_scale_f32 v17, vcc, v42, v14, v42
	v_fma_f32 v18, -v15, v16, 1.0
	v_fmac_f32_e32 v16, v18, v16
	v_mul_f32_e32 v18, v17, v16
	v_fma_f32 v19, -v15, v18, v17
	v_fmac_f32_e32 v18, v19, v16
	v_fma_f32 v15, -v15, v18, v17
	v_div_fmas_f32 v15, v15, v16, v18
	v_div_fixup_f32 v42, v15, v14, v42
	ds_write_b32 v22, v42 offset:16384
	s_waitcnt vmcnt(2)
	v_mul_f32_e32 v14, 0xbfb8aa3b, v43
	v_exp_f32_e32 v14, v14
	s_nop 0
	v_add_f32_e32 v14, 1.0, v14
	v_div_scale_f32 v15, s[10:11], v14, v14, v43
	v_rcp_f32_e32 v16, v15
	v_div_scale_f32 v17, vcc, v43, v14, v43
	v_fma_f32 v18, -v15, v16, 1.0
	v_fmac_f32_e32 v16, v18, v16
	v_mul_f32_e32 v18, v17, v16
	v_fma_f32 v19, -v15, v18, v17
	v_fmac_f32_e32 v18, v19, v16
	v_fma_f32 v15, -v15, v18, v17
	v_div_fmas_f32 v15, v15, v16, v18
	v_div_fixup_f32 v43, v15, v14, v43
	ds_write_b32 v22, v43 offset:17408
	s_waitcnt vmcnt(1)
	v_mul_f32_e32 v14, 0xbfb8aa3b, v44
	v_exp_f32_e32 v14, v14
	s_nop 0
	v_add_f32_e32 v14, 1.0, v14
	v_div_scale_f32 v15, s[10:11], v14, v14, v44
	v_rcp_f32_e32 v16, v15
	v_div_scale_f32 v17, vcc, v44, v14, v44
	v_fma_f32 v18, -v15, v16, 1.0
	v_fmac_f32_e32 v16, v18, v16
	v_mul_f32_e32 v18, v17, v16
	v_fma_f32 v19, -v15, v18, v17
	v_fmac_f32_e32 v18, v19, v16
	v_fma_f32 v15, -v15, v18, v17
	v_div_fmas_f32 v15, v15, v16, v18
	v_div_fixup_f32 v44, v15, v14, v44
	ds_write_b32 v22, v44 offset:18432
	s_waitcnt vmcnt(0)
	v_mul_f32_e32 v14, 0xbfb8aa3b, v45
	v_exp_f32_e32 v14, v14
	s_nop 0
	v_add_f32_e32 v14, 1.0, v14
	v_div_scale_f32 v15, s[10:11], v14, v14, v45
	v_rcp_f32_e32 v16, v15
	v_div_scale_f32 v17, vcc, v45, v14, v45
	v_fma_f32 v18, -v15, v16, 1.0
	v_fmac_f32_e32 v16, v18, v16
	v_mul_f32_e32 v18, v17, v16
	v_fma_f32 v19, -v15, v18, v17
	v_fmac_f32_e32 v18, v19, v16
	v_fma_f32 v15, -v15, v18, v17
	v_div_fmas_f32 v15, v15, v16, v18
	v_div_fixup_f32 v45, v15, v14, v45
	ds_write_b32 v22, v45 offset:19456
.LBB0_534:
	s_mul_hi_i32 s2, s24, 0x2aaaaaab
	s_lshr_b32 s4, s2, 31
	s_ashr_i32 s2, s2, 4
	s_add_i32 s2, s2, s4
	s_mul_i32 s4, s2, 0x60
	s_sub_i32 s4, s24, s4
	s_lshl_b32 s4, s4, 6
	s_ashr_i32 s5, s4, 31
	s_mul_i32 s11, s2, 0x1800000
	s_lshl_b64 s[6:7], s[4:5], 2
	s_mul_hi_i32 s10, s2, 0x1800000
	s_add_u32 s6, s11, s6
	s_addc_u32 s7, s10, s7
	v_mov_b32_e32 v4, 0
	v_lshl_add_u64 v[2:3], v[12:13], 0, s[6:7]
	s_mov_b64 s[6:7], 0
	v_mov_b32_e32 v0, v7
	v_mov_b32_e32 v5, v4
	v_mov_b32_e32 v14, v4
	v_mov_b32_e32 v15, v4
	v_mov_b32_e32 v16, v4
	s_waitcnt lgkmcnt(0)
	s_barrier
	v_readfirstlane_b32 s6, v2
	v_readfirstlane_b32 s7, v3
	v_and_b32_e32 v25, 63, v6
	v_lshlrev_b32_e32 v25, 2, v25
	s_nop 4
	s_nop 0
	global_load_dword v26, v25, s[6:7]
	s_add_u32 s6, s6, 0x6000
	s_addc_u32 s7, s7, 0
	s_nop 0
	global_load_dword v27, v25, s[6:7]
	s_add_u32 s6, s6, 0x6000
	s_addc_u32 s7, s7, 0
	s_nop 0
	global_load_dword v28, v25, s[6:7]
	s_add_u32 s6, s6, 0x6000
	s_addc_u32 s7, s7, 0
	s_nop 0
	global_load_dword v29, v25, s[6:7]
	s_add_u32 s6, s6, 0x6000
	s_addc_u32 s7, s7, 0
	s_nop 0
	global_load_dword v30, v25, s[6:7]
	s_add_u32 s6, s6, 0x6000
	s_addc_u32 s7, s7, 0
	s_nop 0
	global_load_dword v31, v25, s[6:7]
	s_add_u32 s6, s6, 0x6000
	s_addc_u32 s7, s7, 0
	s_nop 0
	global_load_dword v32, v25, s[6:7]
	s_add_u32 s6, s6, 0x6000
	s_addc_u32 s7, s7, 0
	s_nop 0
	global_load_dword v33, v25, s[6:7]
	s_add_u32 s6, s6, 0x6000
	s_addc_u32 s7, s7, 0
	s_nop 0
	global_load_dword v34, v25, s[6:7]
	s_add_u32 s6, s6, 0x6000
	s_addc_u32 s7, s7, 0
	s_nop 0
	global_load_dword v35, v25, s[6:7]
	s_add_u32 s6, s6, 0x6000
	s_addc_u32 s7, s7, 0
	s_nop 0
	global_load_dword v36, v25, s[6:7]
	s_add_u32 s6, s6, 0x6000
	s_addc_u32 s7, s7, 0
	s_nop 0
	global_load_dword v37, v25, s[6:7]
	s_add_u32 s6, s6, 0x6000
	s_addc_u32 s7, s7, 0
	s_nop 0
	global_load_dword v38, v25, s[6:7]
	s_add_u32 s6, s6, 0x6000
	s_addc_u32 s7, s7, 0
	s_nop 0
	global_load_dword v39, v25, s[6:7]
	s_add_u32 s6, s6, 0x6000
	s_addc_u32 s7, s7, 0
	s_nop 0
	global_load_dword v40, v25, s[6:7]
	s_add_u32 s6, s6, 0x6000
	s_addc_u32 s7, s7, 0
	s_nop 0
	global_load_dword v41, v25, s[6:7]
	s_add_u32 s6, s6, 0x6000
	s_addc_u32 s7, s7, 0
	s_mov_b32 s10, 15
.Lmod_loop:
	ds_read_b128 v[228:231], v0
	ds_read_b128 v[232:235], v0 offset:4096
	ds_read_b128 v[236:239], v0 offset:8192
	ds_read_b128 v[240:243], v0 offset:12288
	ds_read_b128 v[244:247], v0 offset:16384
	v_add_u32_e32 v0, 16, v0
	s_waitcnt vmcnt(12) lgkmcnt(0)
	v_fmac_f32_e32 v4, v26, v228
	v_fmac_f32_e32 v5, v26, v232
	v_fmac_f32_e32 v14, v26, v236
	v_fmac_f32_e32 v15, v26, v240
	v_fmac_f32_e32 v16, v26, v244
	v_fmac_f32_e32 v4, v27, v229
	v_fmac_f32_e32 v5, v27, v233
	v_fmac_f32_e32 v14, v27, v237
	v_fmac_f32_e32 v15, v27, v241
	v_fmac_f32_e32 v16, v27, v245
	v_fmac_f32_e32 v4, v28, v230
	v_fmac_f32_e32 v5, v28, v234
	v_fmac_f32_e32 v14, v28, v238
	v_fmac_f32_e32 v15, v28, v242
	v_fmac_f32_e32 v16, v28, v246
	v_fmac_f32_e32 v4, v29, v231
	v_fmac_f32_e32 v5, v29, v235
	v_fmac_f32_e32 v14, v29, v239
	v_fmac_f32_e32 v15, v29, v243
	v_fmac_f32_e32 v16, v29, v247
	s_nop 0
	global_load_dword v26, v25, s[6:7]
	s_add_u32 s6, s6, 0x6000
	s_addc_u32 s7, s7, 0
	s_nop 0
	global_load_dword v27, v25, s[6:7]
	s_add_u32 s6, s6, 0x6000
	s_addc_u32 s7, s7, 0
	s_nop 0
	global_load_dword v28, v25, s[6:7]
	s_add_u32 s6, s6, 0x6000
	s_addc_u32 s7, s7, 0
	s_nop 0
	global_load_dword v29, v25, s[6:7]
	s_add_u32 s6, s6, 0x6000
	s_addc_u32 s7, s7, 0
	ds_read_b128 v[228:231], v0
	ds_read_b128 v[232:235], v0 offset:4096
	ds_read_b128 v[236:239], v0 offset:8192
	ds_read_b128 v[240:243], v0 offset:12288
	ds_read_b128 v[244:247], v0 offset:16384
	v_add_u32_e32 v0, 16, v0
	s_waitcnt vmcnt(12) lgkmcnt(0)
	v_fmac_f32_e32 v4, v30, v228
	v_fmac_f32_e32 v5, v30, v232
	v_fmac_f32_e32 v14, v30, v236
	v_fmac_f32_e32 v15, v30, v240
	v_fmac_f32_e32 v16, v30, v244
	v_fmac_f32_e32 v4, v31, v229
	v_fmac_f32_e32 v5, v31, v233
	v_fmac_f32_e32 v14, v31, v237
	v_fmac_f32_e32 v15, v31, v241
	v_fmac_f32_e32 v16, v31, v245
	v_fmac_f32_e32 v4, v32, v230
	v_fmac_f32_e32 v5, v32, v234
	v_fmac_f32_e32 v14, v32, v238
	v_fmac_f32_e32 v15, v32, v242
	v_fmac_f32_e32 v16, v32, v246
	v_fmac_f32_e32 v4, v33, v231
	v_fmac_f32_e32 v5, v33, v235
	v_fmac_f32_e32 v14, v33, v239
	v_fmac_f32_e32 v15, v33, v243
	v_fmac_f32_e32 v16, v33, v247
	s_nop 0
	global_load_dword v30, v25, s[6:7]
	s_add_u32 s6, s6, 0x6000
	s_addc_u32 s7, s7, 0
	s_nop 0
	global_load_dword v31, v25, s[6:7]
	s_add_u32 s6, s6, 0x6000
	s_addc_u32 s7, s7, 0
	s_nop 0
	global_load_dword v32, v25, s[6:7]
	s_add_u32 s6, s6, 0x6000
	s_addc_u32 s7, s7, 0
	s_nop 0
	global_load_dword v33, v25, s[6:7]
	s_add_u32 s6, s6, 0x6000
	s_addc_u32 s7, s7, 0
	ds_read_b128 v[228:231], v0
	ds_read_b128 v[232:235], v0 offset:4096
	ds_read_b128 v[236:239], v0 offset:8192
	ds_read_b128 v[240:243], v0 offset:12288
	ds_read_b128 v[244:247], v0 offset:16384
	v_add_u32_e32 v0, 16, v0
	s_waitcnt vmcnt(12) lgkmcnt(0)
	v_fmac_f32_e32 v4, v34, v228
	v_fmac_f32_e32 v5, v34, v232
	v_fmac_f32_e32 v14, v34, v236
	v_fmac_f32_e32 v15, v34, v240
	v_fmac_f32_e32 v16, v34, v244
	v_fmac_f32_e32 v4, v35, v229
	v_fmac_f32_e32 v5, v35, v233
	v_fmac_f32_e32 v14, v35, v237
	v_fmac_f32_e32 v15, v35, v241
	v_fmac_f32_e32 v16, v35, v245
	v_fmac_f32_e32 v4, v36, v230
	v_fmac_f32_e32 v5, v36, v234
	v_fmac_f32_e32 v14, v36, v238
	v_fmac_f32_e32 v15, v36, v242
	v_fmac_f32_e32 v16, v36, v246
	v_fmac_f32_e32 v4, v37, v231
	v_fmac_f32_e32 v5, v37, v235
	v_fmac_f32_e32 v14, v37, v239
	v_fmac_f32_e32 v15, v37, v243
	v_fmac_f32_e32 v16, v37, v247
	s_nop 0
	global_load_dword v34, v25, s[6:7]
	s_add_u32 s6, s6, 0x6000
	s_addc_u32 s7, s7, 0
	s_nop 0
	global_load_dword v35, v25, s[6:7]
	s_add_u32 s6, s6, 0x6000
	s_addc_u32 s7, s7, 0
	s_nop 0
	global_load_dword v36, v25, s[6:7]
	s_add_u32 s6, s6, 0x6000
	s_addc_u32 s7, s7, 0
	s_nop 0
	global_load_dword v37, v25, s[6:7]
	s_add_u32 s6, s6, 0x6000
	s_addc_u32 s7, s7, 0
	ds_read_b128 v[228:231], v0
	ds_read_b128 v[232:235], v0 offset:4096
	ds_read_b128 v[236:239], v0 offset:8192
	ds_read_b128 v[240:243], v0 offset:12288
	ds_read_b128 v[244:247], v0 offset:16384
	v_add_u32_e32 v0, 16, v0
	s_waitcnt vmcnt(12) lgkmcnt(0)
	v_fmac_f32_e32 v4, v38, v228
	v_fmac_f32_e32 v5, v38, v232
	v_fmac_f32_e32 v14, v38, v236
	v_fmac_f32_e32 v15, v38, v240
	v_fmac_f32_e32 v16, v38, v244
	v_fmac_f32_e32 v4, v39, v229
	v_fmac_f32_e32 v5, v39, v233
	v_fmac_f32_e32 v14, v39, v237
	v_fmac_f32_e32 v15, v39, v241
	v_fmac_f32_e32 v16, v39, v245
	v_fmac_f32_e32 v4, v40, v230
	v_fmac_f32_e32 v5, v40, v234
	v_fmac_f32_e32 v14, v40, v238
	v_fmac_f32_e32 v15, v40, v242
	v_fmac_f32_e32 v16, v40, v246
	v_fmac_f32_e32 v4, v41, v231
	v_fmac_f32_e32 v5, v41, v235
	v_fmac_f32_e32 v14, v41, v239
	v_fmac_f32_e32 v15, v41, v243
	v_fmac_f32_e32 v16, v41, v247
	s_nop 0
	global_load_dword v38, v25, s[6:7]
	s_add_u32 s6, s6, 0x6000
	s_addc_u32 s7, s7, 0
	s_nop 0
	global_load_dword v39, v25, s[6:7]
	s_add_u32 s6, s6, 0x6000
	s_addc_u32 s7, s7, 0
	s_nop 0
	global_load_dword v40, v25, s[6:7]
	s_add_u32 s6, s6, 0x6000
	s_addc_u32 s7, s7, 0
	s_nop 0
	global_load_dword v41, v25, s[6:7]
	s_add_u32 s6, s6, 0x6000
	s_addc_u32 s7, s7, 0
	s_sub_u32 s10, s10, 1
	s_cmp_lg_u32 s10, 0
	s_cbranch_scc1 .Lmod_loop
	ds_read_b128 v[228:231], v0
	ds_read_b128 v[232:235], v0 offset:4096
	ds_read_b128 v[236:239], v0 offset:8192
	ds_read_b128 v[240:243], v0 offset:12288
	ds_read_b128 v[244:247], v0 offset:16384
	v_add_u32_e32 v0, 16, v0
	s_waitcnt vmcnt(12) lgkmcnt(0)
	v_fmac_f32_e32 v4, v26, v228
	v_fmac_f32_e32 v5, v26, v232
	v_fmac_f32_e32 v14, v26, v236
	v_fmac_f32_e32 v15, v26, v240
	v_fmac_f32_e32 v16, v26, v244
	v_fmac_f32_e32 v4, v27, v229
	v_fmac_f32_e32 v5, v27, v233
	v_fmac_f32_e32 v14, v27, v237
	v_fmac_f32_e32 v15, v27, v241
	v_fmac_f32_e32 v16, v27, v245
	v_fmac_f32_e32 v4, v28, v230
	v_fmac_f32_e32 v5, v28, v234
	v_fmac_f32_e32 v14, v28, v238
	v_fmac_f32_e32 v15, v28, v242
	v_fmac_f32_e32 v16, v28, v246
	v_fmac_f32_e32 v4, v29, v231
	v_fmac_f32_e32 v5, v29, v235
	v_fmac_f32_e32 v14, v29, v239
	v_fmac_f32_e32 v15, v29, v243
	v_fmac_f32_e32 v16, v29, v247
	ds_read_b128 v[228:231], v0
	ds_read_b128 v[232:235], v0 offset:4096
	ds_read_b128 v[236:239], v0 offset:8192
	ds_read_b128 v[240:243], v0 offset:12288
	ds_read_b128 v[244:247], v0 offset:16384
	v_add_u32_e32 v0, 16, v0
	s_waitcnt vmcnt(8) lgkmcnt(0)
	v_fmac_f32_e32 v4, v30, v228
	v_fmac_f32_e32 v5, v30, v232
	v_fmac_f32_e32 v14, v30, v236
	v_fmac_f32_e32 v15, v30, v240
	v_fmac_f32_e32 v16, v30, v244
	v_fmac_f32_e32 v4, v31, v229
	v_fmac_f32_e32 v5, v31, v233
	v_fmac_f32_e32 v14, v31, v237
	v_fmac_f32_e32 v15, v31, v241
	v_fmac_f32_e32 v16, v31, v245
	v_fmac_f32_e32 v4, v32, v230
	v_fmac_f32_e32 v5, v32, v234
	v_fmac_f32_e32 v14, v32, v238
	v_fmac_f32_e32 v15, v32, v242
	v_fmac_f32_e32 v16, v32, v246
	v_fmac_f32_e32 v4, v33, v231
	v_fmac_f32_e32 v5, v33, v235
	v_fmac_f32_e32 v14, v33, v239
	v_fmac_f32_e32 v15, v33, v243
	v_fmac_f32_e32 v16, v33, v247
	ds_read_b128 v[228:231], v0
	ds_read_b128 v[232:235], v0 offset:4096
	ds_read_b128 v[236:239], v0 offset:8192
	ds_read_b128 v[240:243], v0 offset:12288
	ds_read_b128 v[244:247], v0 offset:16384
	v_add_u32_e32 v0, 16, v0
	s_waitcnt vmcnt(4) lgkmcnt(0)
	v_fmac_f32_e32 v4, v34, v228
	v_fmac_f32_e32 v5, v34, v232
	v_fmac_f32_e32 v14, v34, v236
	v_fmac_f32_e32 v15, v34, v240
	v_fmac_f32_e32 v16, v34, v244
	v_fmac_f32_e32 v4, v35, v229
	v_fmac_f32_e32 v5, v35, v233
	v_fmac_f32_e32 v14, v35, v237
	v_fmac_f32_e32 v15, v35, v241
	v_fmac_f32_e32 v16, v35, v245
	v_fmac_f32_e32 v4, v36, v230
	v_fmac_f32_e32 v5, v36, v234
	v_fmac_f32_e32 v14, v36, v238
	v_fmac_f32_e32 v15, v36, v242
	v_fmac_f32_e32 v16, v36, v246
	v_fmac_f32_e32 v4, v37, v231
	v_fmac_f32_e32 v5, v37, v235
	v_fmac_f32_e32 v14, v37, v239
	v_fmac_f32_e32 v15, v37, v243
	v_fmac_f32_e32 v16, v37, v247
	ds_read_b128 v[228:231], v0
	ds_read_b128 v[232:235], v0 offset:4096
	ds_read_b128 v[236:239], v0 offset:8192
	ds_read_b128 v[240:243], v0 offset:12288
	ds_read_b128 v[244:247], v0 offset:16384
	v_add_u32_e32 v0, 16, v0
	s_waitcnt vmcnt(0) lgkmcnt(0)
	v_fmac_f32_e32 v4, v38, v228
	v_fmac_f32_e32 v5, v38, v232
	v_fmac_f32_e32 v14, v38, v236
	v_fmac_f32_e32 v15, v38, v240
	v_fmac_f32_e32 v16, v38, v244
	v_fmac_f32_e32 v4, v39, v229
	v_fmac_f32_e32 v5, v39, v233
	v_fmac_f32_e32 v14, v39, v237
	v_fmac_f32_e32 v15, v39, v241
	v_fmac_f32_e32 v16, v39, v245
	v_fmac_f32_e32 v4, v40, v230
	v_fmac_f32_e32 v5, v40, v234
	v_fmac_f32_e32 v14, v40, v238
	v_fmac_f32_e32 v15, v40, v242
	v_fmac_f32_e32 v16, v40, v246
	v_fmac_f32_e32 v4, v41, v231
	v_fmac_f32_e32 v5, v41, v235
	v_fmac_f32_e32 v14, v41, v239
	v_fmac_f32_e32 v15, v41, v243
	v_fmac_f32_e32 v16, v41, v247
	ds_write2st64_b32 v24, v4, v5 offset0:80 offset1:81
	ds_write2st64_b32 v24, v14, v15 offset0:82 offset1:83
	ds_write_b32 v24, v16 offset:21504
	s_waitcnt lgkmcnt(0)
	s_barrier
	s_and_saveexec_b64 s[6:7], s[8:9]
	s_cbranch_execz .LBB0_478
	s_mul_i32 s10, s2, 0x1800
	s_add_i32 s10, s10, s4
	v_or_b32_e32 v2, s10, v20
	v_ashrrev_i32_e32 v3, 31, v2
	s_mul_i32 s2, s2, 5
	v_lshl_add_u64 v[2:3], v[2:3], 2, s[70:71]
	v_lshl_add_u64 v[4:5], s[4:5], 2, v[8:9]
	s_mov_b64 s[4:5], 0
	v_mov_b32_e32 v0, v23
	v_mov_b32_e32 v14, v6
